# baseline (speedup 1.0000x reference)
;     ...
;     for (int t = 0; t < nt; ++t) {
;       const int cur = t & 1;
;       const char* sa = shm + cur * STAGE_B;
;       const char* sn = shm + (cur ^ 1) * STAGE_B;
;       const bool more = (t + 1 < nt) || (nitem < ntiles);
; #pragma unroll
;       for (int ks = 0; ks < 2; ++ks) {
; #pragma unroll
;         for (int p = 0; p < NP; ++p) {
;           const int q = ks * NP + p;
;           acc[p * 2][0] = __builtin_amdgcn_mfma_f32_16x16x32_bf16(Bq[BDBL ? ks : 0][0], Aq[q & 1][0], acc[p * 2][0], 0, 0, 0);
;           __builtin_amdgcn_sched_barrier(0);
;           if (q == 2 * NP - 1) {
;             WAIT_V(0);
;             __syncthreads();
;             if (more) {
;               if constexpr (BDBL) {
; #pragma unroll
;                 for (int n = 0; n < 4; ++n) Bq[0][n] = *(const bf16x8*)(sn + boff + (n * 2 + 0) * 1024);
;               }
; #pragma unroll
;               for (int i = 0; i < 2; ++i) Aq[0][i] = *(const bf16x8*)(sn + aoff + (i * 2 + 0) * 1024);
;             }
;           } else if (p + 1 < NP) {
; #pragma unroll
;             for (int i = 0; i < 2; ++i) Aq[(q + 1) & 1][i] = *(const bf16x8*)(sa + aoff + (((p + 1) * 2 + i) * 2 + ks) * 1024);
;           } else {
;             if constexpr (BDBL) {
; #pragma unroll
;               for (int n = 0; n < 4; ++n) Bq[1][n] = *(const bf16x8*)(sa + boff + (n * 2 + 1) * 1024);
;             }
; #pragma unroll
;             for (int i = 0; i < 2; ++i) Aq[(q + 1) & 1][i] = *(const bf16x8*)(sa + aoff + (i * 2 + 1) * 1024);
;           }
;           __builtin_amdgcn_sched_barrier(0);
; #pragma unroll
;           for (int i = 0; i < 2; ++i)
; #pragma unroll
;             for (int n = 0; n < 4; ++n)
;               if (i + n > 0)
;                 acc[p * 2 + i][n] = __builtin_amdgcn_mfma_f32_16x16x32_bf16(Bq[BDBL ? ks : 0][n], Aq[q & 1][i], acc[p * 2 + i][n], 0, 0, 0);
;           __builtin_amdgcn_sched_barrier(0);
;           if (q == GLDS_AT) {
;             if (t + 1 < nt) GLDS_STAGE(cur ^ 1, t + 1, Ab, Bb);
;             else if (nitem < ntiles) GLDS_STAGE(0, 0, nAb, nBb);
;             __builtin_amdgcn_sched_barrier(0);
;           }
;           if constexpr (!BDBL) {
;             if (p + 1 == NP) {
;               if (ks == 0) {
; #pragma unroll
;                 for (int n = 0; n < 4; ++n) Bq[0][n] = *(const bf16x8*)(sa + boff + (n * 2 + 1) * 1024);
;               } else if (more) {
.LBB0_741:
	v_lshl_add_u64 v[152:153], s[16:17], 0, v[220:221]
	v_lshl_add_u64 v[154:155], s[14:15], 0, v[220:221]
	s_mov_b64 s[0:1], 0
	s_waitcnt lgkmcnt(0)
	s_nop 0
	v_mfma_f32_16x16x32_bf16 v[148:151], v[4:7], v[20:23], 0
	s_and_b32 s14, s22, 0x10000
	s_xor_b32 s15, s14, 0x10000
	v_add_u32_e32 v168, s14, v222
	v_add_u32_e32 v169, s15, v222
	v_bitop3_b32 v170, s22, v223, v233 bitop3:0xce
	v_or_b32_e32 v171, s14, v223
	ds_read_b128 v[156:159], v168 offset:4096
	ds_read_b128 v[160:163], v168 offset:6144
	v_mfma_f32_16x16x32_bf16 v[144:147], v[0:3], v[20:23], 0
	s_add_i32 s14, s15, s4
	v_lshl_add_u64 v[164:165], v[152:153], 0, s[0:1]
	v_mfma_f32_16x16x32_bf16 v[140:143], v[12:15], v[20:23], 0
	v_lshl_add_u64 v[166:167], v[164:165], 0, s[38:39]
	s_mov_b32 m0, s14
	v_mfma_f32_16x16x32_bf16 v[20:23], v[8:11], v[20:23], 0
	s_add_i32 s15, s14, 0x8000
	global_load_lds_dwordx4 v[166:167], off
	v_mfma_f32_16x16x32_bf16 v[132:135], v[4:7], v[16:19], 0
	v_lshl_add_u64 v[166:167], v[164:165], 0, s[82:83]
	s_add_i32 m0, s14, 0x2000
	v_mfma_f32_16x16x32_bf16 v[128:131], v[0:3], v[16:19], 0
	global_load_lds_dwordx4 v[166:167], off
	v_lshl_add_u64 v[166:167], v[164:165], 0, s[78:79]
	v_mfma_f32_16x16x32_bf16 v[124:127], v[12:15], v[16:19], 0
	s_add_i32 m0, s14, 0x4000
	v_lshl_add_u64 v[164:165], v[164:165], 0, s[2:3]
	v_mfma_f32_16x16x32_bf16 v[16:19], v[8:11], v[16:19], 0
	global_load_lds_dwordx4 v[166:167], off
	s_add_i32 m0, s14, 0x6000
	s_waitcnt lgkmcnt(1)
	v_mfma_f32_16x16x32_bf16 v[116:119], v[4:7], v[156:159], 0
	s_nop 0
	ds_read_b128 v[120:123], v168 offset:8192
	ds_read_b128 v[136:139], v168 offset:10240
	global_load_lds_dwordx4 v[164:165], off
	v_lshl_add_u64 v[164:165], v[154:155], 0, s[0:1]
	v_mfma_f32_16x16x32_bf16 v[112:115], v[0:3], v[156:159], 0
	v_lshl_add_u64 v[166:167], v[164:165], 0, s[38:39]
	s_mov_b32 m0, s15
	v_mfma_f32_16x16x32_bf16 v[108:111], v[12:15], v[156:159], 0
	global_load_lds_dwordx4 v[166:167], off
	v_lshl_add_u64 v[166:167], v[164:165], 0, s[82:83]
	v_mfma_f32_16x16x32_bf16 v[104:107], v[8:11], v[156:159], 0
	s_add_i32 m0, s14, 0xa000
	s_waitcnt lgkmcnt(2)
	v_mfma_f32_16x16x32_bf16 v[100:103], v[4:7], v[160:163], 0
	global_load_lds_dwordx4 v[166:167], off
	v_lshl_add_u64 v[166:167], v[164:165], 0, s[78:79]
	v_mfma_f32_16x16x32_bf16 v[96:99], v[0:3], v[160:163], 0
	s_add_i32 m0, s14, 0xc000
	v_lshl_add_u64 v[164:165], v[164:165], 0, s[2:3]
	v_mfma_f32_16x16x32_bf16 v[92:95], v[12:15], v[160:163], 0
	global_load_lds_dwordx4 v[166:167], off
	s_add_i32 m0, s14, 0xe000
	v_mfma_f32_16x16x32_bf16 v[88:91], v[8:11], v[160:163], 0
	global_load_lds_dwordx4 v[164:165], off
	s_waitcnt lgkmcnt(1)
	v_mfma_f32_16x16x32_bf16 v[84:87], v[4:7], v[120:123], 0
	ds_read_b128 v[156:159], v168 offset:12288
	ds_read_b128 v[160:163], v168 offset:14336
	ds_read_b128 v[172:175], v171 offset:33792
	ds_read_b128 v[176:179], v171 offset:35840
	ds_read_b128 v[180:183], v171 offset:37888
	ds_read_b128 v[184:187], v171 offset:39936
	v_mfma_f32_16x16x32_bf16 v[80:83], v[0:3], v[120:123], 0
	v_mfma_f32_16x16x32_bf16 v[76:79], v[12:15], v[120:123], 0
	v_mfma_f32_16x16x32_bf16 v[72:75], v[8:11], v[120:123], 0
	s_waitcnt lgkmcnt(6)
	v_mfma_f32_16x16x32_bf16 v[68:71], v[4:7], v[136:139], 0
	v_mfma_f32_16x16x32_bf16 v[64:67], v[0:3], v[136:139], 0
	v_mfma_f32_16x16x32_bf16 v[60:63], v[12:15], v[136:139], 0
	v_mfma_f32_16x16x32_bf16 v[56:59], v[8:11], v[136:139], 0
	s_waitcnt lgkmcnt(5)
	v_mfma_f32_16x16x32_bf16 v[52:55], v[4:7], v[156:159], 0
	ds_read_b128 v[120:123], v168 offset:1024
	ds_read_b128 v[164:167], v168 offset:3072
	v_mfma_f32_16x16x32_bf16 v[48:51], v[0:3], v[156:159], 0
	v_mfma_f32_16x16x32_bf16 v[44:47], v[12:15], v[156:159], 0
	v_mfma_f32_16x16x32_bf16 v[40:43], v[8:11], v[156:159], 0
	s_waitcnt lgkmcnt(6)
	v_mfma_f32_16x16x32_bf16 v[4:7], v[4:7], v[160:163], 0
	v_mfma_f32_16x16x32_bf16 v[0:3], v[0:3], v[160:163], 0
	v_mfma_f32_16x16x32_bf16 v[12:15], v[12:15], v[160:163], 0
	v_mfma_f32_16x16x32_bf16 v[8:11], v[8:11], v[160:163], 0
	s_waitcnt lgkmcnt(0)
	v_mfma_f32_16x16x32_bf16 v[148:151], v[172:175], v[120:123], v[148:151]
	ds_read_b128 v[32:35], v168 offset:5120
	ds_read_b128 v[36:39], v168 offset:7168
	v_mfma_f32_16x16x32_bf16 v[144:147], v[176:179], v[120:123], v[144:147]
	v_mfma_f32_16x16x32_bf16 v[140:143], v[180:183], v[120:123], v[140:143]
	v_mfma_f32_16x16x32_bf16 v[136:139], v[184:187], v[120:123], v[20:23]
	v_mfma_f32_16x16x32_bf16 v[132:135], v[172:175], v[164:167], v[132:135]
	v_mfma_f32_16x16x32_bf16 v[128:131], v[176:179], v[164:167], v[128:131]
	v_mfma_f32_16x16x32_bf16 v[124:127], v[180:183], v[164:167], v[124:127]
	v_mfma_f32_16x16x32_bf16 v[120:123], v[184:187], v[164:167], v[16:19]
	s_waitcnt lgkmcnt(1)
	v_mfma_f32_16x16x32_bf16 v[116:119], v[172:175], v[32:35], v[116:119]
	s_nop 0
	ds_read_b128 v[16:19], v168 offset:9216
	ds_read_b128 v[20:23], v168 offset:11264
	v_mfma_f32_16x16x32_bf16 v[112:115], v[176:179], v[32:35], v[112:115]
	v_mfma_f32_16x16x32_bf16 v[108:111], v[180:183], v[32:35], v[108:111]
	v_mfma_f32_16x16x32_bf16 v[104:107], v[184:187], v[32:35], v[104:107]
	s_waitcnt lgkmcnt(2)
	v_mfma_f32_16x16x32_bf16 v[100:103], v[172:175], v[36:39], v[100:103]
	v_mfma_f32_16x16x32_bf16 v[96:99], v[176:179], v[36:39], v[96:99]
	v_mfma_f32_16x16x32_bf16 v[92:95], v[180:183], v[36:39], v[92:95]
	v_mfma_f32_16x16x32_bf16 v[88:91], v[184:187], v[36:39], v[88:91]
	s_waitcnt lgkmcnt(1)
	v_mfma_f32_16x16x32_bf16 v[84:87], v[172:175], v[16:19], v[84:87]
	ds_read_b128 v[32:35], v168 offset:13312
	ds_read_b128 v[164:167], v168 offset:15360
	v_mfma_f32_16x16x32_bf16 v[80:83], v[176:179], v[16:19], v[80:83]
	v_mfma_f32_16x16x32_bf16 v[76:79], v[180:183], v[16:19], v[76:79]
	v_mfma_f32_16x16x32_bf16 v[72:75], v[184:187], v[16:19], v[72:75]
	s_waitcnt lgkmcnt(2)
	v_mfma_f32_16x16x32_bf16 v[68:71], v[172:175], v[20:23], v[68:71]
	v_mfma_f32_16x16x32_bf16 v[64:67], v[176:179], v[20:23], v[64:67]
	v_mfma_f32_16x16x32_bf16 v[60:63], v[180:183], v[20:23], v[60:63]
	v_mfma_f32_16x16x32_bf16 v[56:59], v[184:187], v[20:23], v[56:59]
	s_waitcnt lgkmcnt(1)
	v_mfma_f32_16x16x32_bf16 v[52:55], v[172:175], v[32:35], v[52:55]
	s_waitcnt vmcnt(0)
	s_waitcnt lgkmcnt(0)
	s_barrier
	ds_read_b128 v[20:23], v169
	ds_read_b128 v[16:19], v169 offset:2048
	v_mfma_f32_16x16x32_bf16 v[48:51], v[176:179], v[32:35], v[48:51]
	v_mfma_f32_16x16x32_bf16 v[44:47], v[180:183], v[32:35], v[44:47]
	v_mfma_f32_16x16x32_bf16 v[40:43], v[184:187], v[32:35], v[40:43]
	v_mfma_f32_16x16x32_bf16 v[36:39], v[172:175], v[164:167], v[4:7]
	v_mfma_f32_16x16x32_bf16 v[32:35], v[176:179], v[164:167], v[0:3]
	v_mfma_f32_16x16x32_bf16 v[28:31], v[180:183], v[164:167], v[12:15]
	v_mfma_f32_16x16x32_bf16 v[24:27], v[184:187], v[164:167], v[8:11]
	ds_read_b128 v[4:7], v170 offset:32768
	ds_read_b128 v[0:3], v170 offset:34816
	ds_read_b128 v[12:15], v170 offset:36864
	ds_read_b128 v[8:11], v170 offset:38912
	s_add_u32 s0, s0, 0x80
	s_addc_u32 s1, s1, 0
	s_add_i32 s22, s22, 0x10000
;     ...
;     for (int t = 0; t < nt; ++t) {
;       const int cur = t & 1;
;       const char* sa = shm + cur * STAGE_B;
;       const char* sn = shm + (cur ^ 1) * STAGE_B;
;       const bool more = (t + 1 < nt) || (nitem < ntiles);
; #pragma unroll
;       for (int ks = 0; ks < 2; ++ks) {
; #pragma unroll
;         for (int p = 0; p < NP; ++p) {
;           const int q = ks * NP + p;
;           acc[p * 2][0] = __builtin_amdgcn_mfma_f32_16x16x32_bf16(Bq[BDBL ? ks : 0][0], Aq[q & 1][0], acc[p * 2][0], 0, 0, 0);
;           __builtin_amdgcn_sched_barrier(0);
;           if (q == 2 * NP - 1) {
;             WAIT_V(0);
;             __syncthreads();
;             if (more) {
;               if constexpr (BDBL) {
; #pragma unroll
;                 for (int n = 0; n < 4; ++n) Bq[0][n] = *(const bf16x8*)(sn + boff + (n * 2 + 0) * 1024);
;               }
; #pragma unroll
;               for (int i = 0; i < 2; ++i) Aq[0][i] = *(const bf16x8*)(sn + aoff + (i * 2 + 0) * 1024);
;             }
;           } else if (p + 1 < NP) {
; #pragma unroll
;             for (int i = 0; i < 2; ++i) Aq[(q + 1) & 1][i] = *(const bf16x8*)(sa + aoff + (((p + 1) * 2 + i) * 2 + ks) * 1024);
;           } else {
;             if constexpr (BDBL) {
; #pragma unroll
;               for (int n = 0; n < 4; ++n) Bq[1][n] = *(const bf16x8*)(sa + boff + (n * 2 + 1) * 1024);
;             }
; #pragma unroll
;             for (int i = 0; i < 2; ++i) Aq[(q + 1) & 1][i] = *(const bf16x8*)(sa + aoff + (i * 2 + 1) * 1024);
;           }
;           __builtin_amdgcn_sched_barrier(0);
; #pragma unroll
;           for (int i = 0; i < 2; ++i)
; #pragma unroll
;             for (int n = 0; n < 4; ++n)
;               if (i + n > 0)
;                 acc[p * 2 + i][n] = __builtin_amdgcn_mfma_f32_16x16x32_bf16(Bq[BDBL ? ks : 0][n], Aq[q & 1][i], acc[p * 2 + i][n], 0, 0, 0);
;           __builtin_amdgcn_sched_barrier(0);
;           if (q == GLDS_AT) {
;             if (t + 1 < nt) GLDS_STAGE(cur ^ 1, t + 1, Ab, Bb);
;             else if (nitem < ntiles) GLDS_STAGE(0, 0, nAb, nBb);
;             __builtin_amdgcn_sched_barrier(0);
;           }
;           if constexpr (!BDBL) {
;             if (p + 1 == NP) {
;               if (ks == 0) {
; #pragma unroll
;                 for (int n = 0; n < 4; ++n) Bq[0][n] = *(const bf16x8*)(sa + boff + (n * 2 + 1) * 1024);
;               } else if (more) {
.LBB0_742:
	s_waitcnt lgkmcnt(0)
	s_nop 0
	v_mfma_f32_16x16x32_bf16 v[148:151], v[4:7], v[20:23], v[148:151]
	s_and_b32 s14, s22, 0x10000
	s_xor_b32 s15, s14, 0x10000
	v_add_u32_e32 v168, s14, v222
	v_add_u32_e32 v169, s15, v222
	v_bitop3_b32 v170, s22, v223, v233 bitop3:0xce
	v_or_b32_e32 v171, s14, v223
	ds_read_b128 v[156:159], v168 offset:4096
	ds_read_b128 v[160:163], v168 offset:6144
	v_mfma_f32_16x16x32_bf16 v[144:147], v[0:3], v[20:23], v[144:147]
	s_add_i32 s14, s15, s4
	v_lshl_add_u64 v[164:165], v[152:153], 0, s[0:1]
	v_mfma_f32_16x16x32_bf16 v[140:143], v[12:15], v[20:23], v[140:143]
	v_lshl_add_u64 v[166:167], v[164:165], 0, s[38:39]
	s_mov_b32 m0, s14
	v_mfma_f32_16x16x32_bf16 v[20:23], v[8:11], v[20:23], v[136:139]
	s_add_i32 s15, s14, 0x8000
	global_load_lds_dwordx4 v[166:167], off
	v_mfma_f32_16x16x32_bf16 v[132:135], v[4:7], v[16:19], v[132:135]
	v_lshl_add_u64 v[166:167], v[164:165], 0, s[82:83]
	s_add_i32 m0, s14, 0x2000
	v_mfma_f32_16x16x32_bf16 v[128:131], v[0:3], v[16:19], v[128:131]
	global_load_lds_dwordx4 v[166:167], off
	v_lshl_add_u64 v[166:167], v[164:165], 0, s[78:79]
	v_mfma_f32_16x16x32_bf16 v[124:127], v[12:15], v[16:19], v[124:127]
	s_add_i32 m0, s14, 0x4000
	v_lshl_add_u64 v[164:165], v[164:165], 0, s[2:3]
	v_mfma_f32_16x16x32_bf16 v[16:19], v[8:11], v[16:19], v[120:123]
	global_load_lds_dwordx4 v[166:167], off
	s_add_i32 m0, s14, 0x6000
	s_waitcnt lgkmcnt(1)
	v_mfma_f32_16x16x32_bf16 v[116:119], v[4:7], v[156:159], v[116:119]
	s_nop 0
	ds_read_b128 v[120:123], v168 offset:8192
	ds_read_b128 v[136:139], v168 offset:10240
	global_load_lds_dwordx4 v[164:165], off
	v_lshl_add_u64 v[164:165], v[154:155], 0, s[0:1]
	v_mfma_f32_16x16x32_bf16 v[112:115], v[0:3], v[156:159], v[112:115]
	v_lshl_add_u64 v[166:167], v[164:165], 0, s[38:39]
	s_mov_b32 m0, s15
	v_mfma_f32_16x16x32_bf16 v[108:111], v[12:15], v[156:159], v[108:111]
	global_load_lds_dwordx4 v[166:167], off
	v_lshl_add_u64 v[166:167], v[164:165], 0, s[82:83]
	v_mfma_f32_16x16x32_bf16 v[104:107], v[8:11], v[156:159], v[104:107]
	s_add_i32 m0, s14, 0xa000
	s_waitcnt lgkmcnt(2)
	v_mfma_f32_16x16x32_bf16 v[100:103], v[4:7], v[160:163], v[100:103]
	global_load_lds_dwordx4 v[166:167], off
	v_lshl_add_u64 v[166:167], v[164:165], 0, s[78:79]
	v_mfma_f32_16x16x32_bf16 v[96:99], v[0:3], v[160:163], v[96:99]
	s_add_i32 m0, s14, 0xc000
	v_lshl_add_u64 v[164:165], v[164:165], 0, s[2:3]
	v_mfma_f32_16x16x32_bf16 v[92:95], v[12:15], v[160:163], v[92:95]
	global_load_lds_dwordx4 v[166:167], off
	s_add_i32 m0, s14, 0xe000
	v_mfma_f32_16x16x32_bf16 v[88:91], v[8:11], v[160:163], v[88:91]
	global_load_lds_dwordx4 v[164:165], off
	s_waitcnt lgkmcnt(1)
	v_mfma_f32_16x16x32_bf16 v[84:87], v[4:7], v[120:123], v[84:87]
	ds_read_b128 v[156:159], v168 offset:12288
	ds_read_b128 v[160:163], v168 offset:14336
	ds_read_b128 v[172:175], v171 offset:33792
	ds_read_b128 v[176:179], v171 offset:35840
	ds_read_b128 v[180:183], v171 offset:37888
	ds_read_b128 v[184:187], v171 offset:39936
	v_mfma_f32_16x16x32_bf16 v[80:83], v[0:3], v[120:123], v[80:83]
	v_mfma_f32_16x16x32_bf16 v[76:79], v[12:15], v[120:123], v[76:79]
	v_mfma_f32_16x16x32_bf16 v[72:75], v[8:11], v[120:123], v[72:75]
	s_waitcnt lgkmcnt(6)
	v_mfma_f32_16x16x32_bf16 v[68:71], v[4:7], v[136:139], v[68:71]
	v_mfma_f32_16x16x32_bf16 v[64:67], v[0:3], v[136:139], v[64:67]
	v_mfma_f32_16x16x32_bf16 v[60:63], v[12:15], v[136:139], v[60:63]
	v_mfma_f32_16x16x32_bf16 v[56:59], v[8:11], v[136:139], v[56:59]
	s_waitcnt lgkmcnt(5)
	v_mfma_f32_16x16x32_bf16 v[52:55], v[4:7], v[156:159], v[52:55]
	ds_read_b128 v[120:123], v168 offset:1024
	ds_read_b128 v[164:167], v168 offset:3072
	v_mfma_f32_16x16x32_bf16 v[48:51], v[0:3], v[156:159], v[48:51]
	v_mfma_f32_16x16x32_bf16 v[44:47], v[12:15], v[156:159], v[44:47]
	v_mfma_f32_16x16x32_bf16 v[40:43], v[8:11], v[156:159], v[40:43]
	s_waitcnt lgkmcnt(6)
	v_mfma_f32_16x16x32_bf16 v[4:7], v[4:7], v[160:163], v[36:39]
	v_mfma_f32_16x16x32_bf16 v[0:3], v[0:3], v[160:163], v[32:35]
	v_mfma_f32_16x16x32_bf16 v[12:15], v[12:15], v[160:163], v[28:31]
	v_mfma_f32_16x16x32_bf16 v[8:11], v[8:11], v[160:163], v[24:27]
	s_waitcnt lgkmcnt(0)
	v_mfma_f32_16x16x32_bf16 v[148:151], v[172:175], v[120:123], v[148:151]
	ds_read_b128 v[32:35], v168 offset:5120
	ds_read_b128 v[36:39], v168 offset:7168
	v_mfma_f32_16x16x32_bf16 v[144:147], v[176:179], v[120:123], v[144:147]
	v_mfma_f32_16x16x32_bf16 v[140:143], v[180:183], v[120:123], v[140:143]
	v_mfma_f32_16x16x32_bf16 v[136:139], v[184:187], v[120:123], v[20:23]
	v_mfma_f32_16x16x32_bf16 v[132:135], v[172:175], v[164:167], v[132:135]
	v_mfma_f32_16x16x32_bf16 v[128:131], v[176:179], v[164:167], v[128:131]
	v_mfma_f32_16x16x32_bf16 v[124:127], v[180:183], v[164:167], v[124:127]
	v_mfma_f32_16x16x32_bf16 v[120:123], v[184:187], v[164:167], v[16:19]
	s_waitcnt lgkmcnt(1)
	v_mfma_f32_16x16x32_bf16 v[116:119], v[172:175], v[32:35], v[116:119]
	s_nop 0
	ds_read_b128 v[16:19], v168 offset:9216
	ds_read_b128 v[20:23], v168 offset:11264
	v_mfma_f32_16x16x32_bf16 v[112:115], v[176:179], v[32:35], v[112:115]
	v_mfma_f32_16x16x32_bf16 v[108:111], v[180:183], v[32:35], v[108:111]
	v_mfma_f32_16x16x32_bf16 v[104:107], v[184:187], v[32:35], v[104:107]
	s_waitcnt lgkmcnt(2)
	v_mfma_f32_16x16x32_bf16 v[100:103], v[172:175], v[36:39], v[100:103]
	v_mfma_f32_16x16x32_bf16 v[96:99], v[176:179], v[36:39], v[96:99]
	v_mfma_f32_16x16x32_bf16 v[92:95], v[180:183], v[36:39], v[92:95]
	v_mfma_f32_16x16x32_bf16 v[88:91], v[184:187], v[36:39], v[88:91]
	s_waitcnt lgkmcnt(1)
	v_mfma_f32_16x16x32_bf16 v[84:87], v[172:175], v[16:19], v[84:87]
	ds_read_b128 v[32:35], v168 offset:13312
	ds_read_b128 v[164:167], v168 offset:15360
	v_mfma_f32_16x16x32_bf16 v[80:83], v[176:179], v[16:19], v[80:83]
	v_mfma_f32_16x16x32_bf16 v[76:79], v[180:183], v[16:19], v[76:79]
	v_mfma_f32_16x16x32_bf16 v[72:75], v[184:187], v[16:19], v[72:75]
	s_waitcnt lgkmcnt(2)
	v_mfma_f32_16x16x32_bf16 v[68:71], v[172:175], v[20:23], v[68:71]
	v_mfma_f32_16x16x32_bf16 v[64:67], v[176:179], v[20:23], v[64:67]
	v_mfma_f32_16x16x32_bf16 v[60:63], v[180:183], v[20:23], v[60:63]
	v_mfma_f32_16x16x32_bf16 v[56:59], v[184:187], v[20:23], v[56:59]
	s_waitcnt lgkmcnt(1)
	v_mfma_f32_16x16x32_bf16 v[52:55], v[172:175], v[32:35], v[52:55]
	s_waitcnt vmcnt(0)
	s_waitcnt lgkmcnt(0)
	s_barrier
;     ...
;     for (int t = 0; t < nt; ++t) {
;       const int cur = t & 1;
;       const char* sa = shm + cur * STAGE_B;
;       const char* sn = shm + (cur ^ 1) * STAGE_B;
;       const bool more = (t + 1 < nt) || (nitem < ntiles);
; #pragma unroll
;       for (int ks = 0; ks < 2; ++ks) {
; #pragma unroll
;         for (int p = 0; p < NP; ++p) {
;           const int q = ks * NP + p;
;           acc[p * 2][0] = __builtin_amdgcn_mfma_f32_16x16x32_bf16(Bq[BDBL ? ks : 0][0], Aq[q & 1][0], acc[p * 2][0], 0, 0, 0);
;           __builtin_amdgcn_sched_barrier(0);
;           if (q == 2 * NP - 1) {
;             WAIT_V(0);
;             __syncthreads();
;             if (more) {
;               if constexpr (BDBL) {
; #pragma unroll
;                 for (int n = 0; n < 4; ++n) Bq[0][n] = *(const bf16x8*)(sn + boff + (n * 2 + 0) * 1024);
;               }
; #pragma unroll
;               for (int i = 0; i < 2; ++i) Aq[0][i] = *(const bf16x8*)(sn + aoff + (i * 2 + 0) * 1024);
;             }
;           } else if (p + 1 < NP) {
; #pragma unroll
;             for (int i = 0; i < 2; ++i) Aq[(q + 1) & 1][i] = *(const bf16x8*)(sa + aoff + (((p + 1) * 2 + i) * 2 + ks) * 1024);
;           } else {
;             if constexpr (BDBL) {
; #pragma unroll
;               for (int n = 0; n < 4; ++n) Bq[1][n] = *(const bf16x8*)(sa + boff + (n * 2 + 1) * 1024);
;             }
; #pragma unroll
;             for (int i = 0; i < 2; ++i) Aq[(q + 1) & 1][i] = *(const bf16x8*)(sa + aoff + (i * 2 + 1) * 1024);
;           }
;           __builtin_amdgcn_sched_barrier(0);
; #pragma unroll
;           for (int i = 0; i < 2; ++i)
; #pragma unroll
;             for (int n = 0; n < 4; ++n)
;               if (i + n > 0)
;                 acc[p * 2 + i][n] = __builtin_amdgcn_mfma_f32_16x16x32_bf16(Bq[BDBL ? ks : 0][n], Aq[q & 1][i], acc[p * 2 + i][n], 0, 0, 0);
;           __builtin_amdgcn_sched_barrier(0);
;           if (q == GLDS_AT) {
;             if (t + 1 < nt) GLDS_STAGE(cur ^ 1, t + 1, Ab, Bb);
;             else if (nitem < ntiles) GLDS_STAGE(0, 0, nAb, nBb);
;             __builtin_amdgcn_sched_barrier(0);
;           }
;           if constexpr (!BDBL) {
;             if (p + 1 == NP) {
;               if (ks == 0) {
; #pragma unroll
;                 for (int n = 0; n < 4; ++n) Bq[0][n] = *(const bf16x8*)(sa + boff + (n * 2 + 1) * 1024);
;               } else if (more) {
	ds_read_b128 v[20:23], v169
	ds_read_b128 v[16:19], v169 offset:2048
	v_mfma_f32_16x16x32_bf16 v[48:51], v[176:179], v[32:35], v[48:51]
	v_mfma_f32_16x16x32_bf16 v[44:47], v[180:183], v[32:35], v[44:47]
	v_mfma_f32_16x16x32_bf16 v[40:43], v[184:187], v[32:35], v[40:43]
	v_mfma_f32_16x16x32_bf16 v[36:39], v[172:175], v[164:167], v[4:7]
	v_mfma_f32_16x16x32_bf16 v[32:35], v[176:179], v[164:167], v[0:3]
	v_mfma_f32_16x16x32_bf16 v[28:31], v[180:183], v[164:167], v[12:15]
	v_mfma_f32_16x16x32_bf16 v[24:27], v[184:187], v[164:167], v[8:11]
	ds_read_b128 v[4:7], v170 offset:32768
	ds_read_b128 v[0:3], v170 offset:34816
	ds_read_b128 v[12:15], v170 offset:36864
	ds_read_b128 v[8:11], v170 offset:38912
	s_add_u32 s0, s0, 0x80
	s_addc_u32 s1, s1, 0
	s_add_i32 s22, s22, 0x10000
	s_cmpk_eq_i32 s0, 0x780
	s_cbranch_scc0 .LBB0_742
	s_waitcnt lgkmcnt(3)
	v_mfma_f32_16x16x32_bf16 v[148:151], v[4:7], v[20:23], v[148:151]
	v_add_u32_e32 v224, 0x10000, v222
	ds_read_b128 v[152:155], v224 offset:4096
	ds_read_b128 v[156:159], v224 offset:6144
	s_waitcnt lgkmcnt(4)
	v_mfma_f32_16x16x32_bf16 v[164:167], v[0:3], v[20:23], v[144:147]
	s_waitcnt lgkmcnt(3)
	v_mfma_f32_16x16x32_bf16 v[140:143], v[12:15], v[20:23], v[140:143]
	s_waitcnt lgkmcnt(2)
	v_mfma_f32_16x16x32_bf16 v[20:23], v[8:11], v[20:23], v[136:139]
	v_mfma_f32_16x16x32_bf16 v[132:135], v[4:7], v[16:19], v[132:135]
	v_mfma_f32_16x16x32_bf16 v[168:171], v[0:3], v[16:19], v[128:131]
	v_mfma_f32_16x16x32_bf16 v[124:127], v[12:15], v[16:19], v[124:127]
	v_mfma_f32_16x16x32_bf16 v[16:19], v[8:11], v[16:19], v[120:123]
	s_waitcnt lgkmcnt(1)
	v_mfma_f32_16x16x32_bf16 v[116:119], v[4:7], v[152:155], v[116:119]
	s_nop 0
	ds_read_b128 v[120:123], v224 offset:8192
	ds_read_b128 v[128:131], v224 offset:10240
	v_mfma_f32_16x16x32_bf16 v[172:175], v[0:3], v[152:155], v[112:115]
	v_mfma_f32_16x16x32_bf16 v[108:111], v[12:15], v[152:155], v[108:111]
	v_mfma_f32_16x16x32_bf16 v[176:179], v[8:11], v[152:155], v[104:107]
	s_waitcnt lgkmcnt(2)
	v_mfma_f32_16x16x32_bf16 v[100:103], v[4:7], v[156:159], v[100:103]
	v_mfma_f32_16x16x32_bf16 v[180:183], v[0:3], v[156:159], v[96:99]
	v_mfma_f32_16x16x32_bf16 v[92:95], v[12:15], v[156:159], v[92:95]
	v_mfma_f32_16x16x32_bf16 v[184:187], v[8:11], v[156:159], v[88:91]
	s_waitcnt lgkmcnt(1)
	v_mfma_f32_16x16x32_bf16 v[84:87], v[4:7], v[120:123], v[84:87]
	s_nop 0
	ds_read_b128 v[88:91], v224 offset:12288
	ds_read_b128 v[96:99], v224 offset:14336
	v_mfma_f32_16x16x32_bf16 v[188:191], v[0:3], v[120:123], v[80:83]
	v_mfma_f32_16x16x32_bf16 v[76:79], v[12:15], v[120:123], v[76:79]
	v_mfma_f32_16x16x32_bf16 v[192:195], v[8:11], v[120:123], v[72:75]
	s_waitcnt lgkmcnt(2)
	v_mfma_f32_16x16x32_bf16 v[68:71], v[4:7], v[128:131], v[68:71]
	v_mfma_f32_16x16x32_bf16 v[196:199], v[0:3], v[128:131], v[64:67]
	v_mfma_f32_16x16x32_bf16 v[60:63], v[12:15], v[128:131], v[60:63]
	v_mfma_f32_16x16x32_bf16 v[200:203], v[8:11], v[128:131], v[56:59]
	s_waitcnt lgkmcnt(1)
	v_mfma_f32_16x16x32_bf16 v[204:207], v[4:7], v[88:91], v[52:55]
	ds_read_b128 v[64:67], v224 offset:1024
	ds_read_b128 v[56:59], v224 offset:3072
	v_mfma_f32_16x16x32_bf16 v[52:55], v[0:3], v[88:91], v[48:51]
	v_mfma_f32_16x16x32_bf16 v[44:47], v[12:15], v[88:91], v[44:47]
	v_mfma_f32_16x16x32_bf16 v[152:155], v[8:11], v[88:91], v[40:43]
	s_waitcnt lgkmcnt(2)
	v_mfma_f32_16x16x32_bf16 v[36:39], v[4:7], v[96:99], v[36:39]
	v_mfma_f32_16x16x32_bf16 v[156:159], v[0:3], v[96:99], v[32:35]
	v_mfma_f32_16x16x32_bf16 v[28:31], v[12:15], v[96:99], v[28:31]
	v_mfma_f32_16x16x32_bf16 v[160:163], v[8:11], v[96:99], v[24:27]
	v_cndmask_b32_e64 v0, 0, 1, s[6:7]
	v_cmp_ne_u32_e64 s[0:1], 1, v0
	s_andn2_b64 vcc, exec, s[6:7]
	s_cbranch_vccnz .LBB0_745
	s_mov_b32 m0, s4
	v_lshl_add_u64 v[0:1], s[8:9], 0, v[208:209]
	v_lshl_add_u64 v[4:5], v[0:1], 0, s[76:77]
	global_load_lds_dwordx4 v[0:1], off
	s_add_i32 m0, s4, 0x2000
	v_lshl_add_u64 v[6:7], v[0:1], 0, s[96:97]
	global_load_lds_dwordx4 v[4:5], off
	s_add_i32 m0, s4, 0x4000
	v_lshl_add_u64 v[8:9], v[0:1], 0, s[70:71]
	global_load_lds_dwordx4 v[6:7], off
	s_add_i32 m0, s4, 0x6000
	v_lshl_add_u64 v[2:3], s[10:11], 0, v[208:209]
	global_load_lds_dwordx4 v[8:9], off
	s_add_i32 m0, s4, 0x8000
	v_lshl_add_u64 v[10:11], v[2:3], 0, s[76:77]
	global_load_lds_dwordx4 v[2:3], off
	s_add_i32 m0, s4, 0xa000
	v_lshl_add_u64 v[12:13], v[2:3], 0, s[96:97]
	global_load_lds_dwordx4 v[10:11], off
	s_add_i32 m0, s4, 0xc000
	v_lshl_add_u64 v[14:15], v[2:3], 0, s[70:71]
	global_load_lds_dwordx4 v[12:13], off
	s_add_i32 m0, s4, 0xe000
	s_nop 0
	global_load_lds_dwordx4 v[14:15], off

; __device__ __forceinline__ void hgrn_phase(const Params& P, char* shm, int lbid) {
;     ...
;     f32x4 Sacc[8];
; #pragma unroll
;     for (int vt = 0; vt < 8; ++vt) Sacc[vt] = f32x4{0.f, 0.f, 0.f, 0.f};
;     char* sb = shm + SB0;
;     HG_ISSUE(0);
;     HG_PRODUCE(0);
;     HG_ISSUE(1);
;     for (int c = 0; c < NCH; ++c) {
.LBB0_907:
	s_or_b64 exec, exec, s[0:1]
	v_lshlrev_b32_e32 v107, 1, v15
	s_movk_i32 s0, 0x50
	v_mad_u32_u24 v4, v16, s0, v107
	v_readlane_b32 s0, v254, 7
	s_waitcnt vmcnt(0)
	ds_write_b16 v4, v0 offset:27648
	ds_write_b16_d16_hi v4, v0 offset:27728
	ds_write_b16 v4, v1 offset:27808
	ds_write_b16_d16_hi v4, v1 offset:27888
	ds_write_b16 v4, v2 offset:27968
	ds_write_b16_d16_hi v4, v2 offset:28048
	ds_write_b16 v4, v3 offset:28128
	ds_write_b16_d16_hi v4, v3 offset:28208
	v_add_u32_e32 v0, s0, v114
	v_mul_u32_u24_e32 v106, 0x50, v16
	v_ashrrev_i32_e32 v1, 31, v0
	v_add_u32_e32 v4, s0, v94
	v_add_u32_e32 v8, s0, v95
	v_add_u32_e32 v16, s0, v96
	v_lshlrev_b64 v[0:1], 9, v[0:1]
	v_ashrrev_i32_e32 v5, 31, v4
	v_ashrrev_i32_e32 v9, 31, v8
	s_waitcnt lgkmcnt(14)
	v_ashrrev_i32_e32 v17, 31, v16
	v_lshl_add_u64 v[0:1], v[0:1], 0, v[72:73]
	v_lshlrev_b64 v[4:5], 9, v[4:5]
	v_lshlrev_b64 v[8:9], 9, v[8:9]
	v_lshlrev_b64 v[16:17], 9, v[16:17]
	v_lshl_add_u64 v[2:3], v[0:1], 2, s[34:35]
	v_lshl_add_u64 v[0:1], v[0:1], 1, s[62:63]
	v_lshl_add_u64 v[4:5], v[4:5], 0, v[72:73]
	v_lshl_add_u64 v[8:9], v[8:9], 0, v[72:73]
	v_lshl_add_u64 v[16:17], v[16:17], 0, v[72:73]
	v_lshl_add_u64 v[6:7], v[4:5], 2, s[34:35]
	v_lshl_add_u64 v[4:5], v[4:5], 1, s[62:63]
	v_lshl_add_u64 v[10:11], v[8:9], 2, s[34:35]
	v_lshl_add_u64 v[8:9], v[8:9], 1, s[62:63]
	v_lshl_add_u64 v[18:19], v[16:17], 2, s[34:35]
	v_lshl_add_u64 v[16:17], v[16:17], 1, s[62:63]
	global_load_dword v84, v[2:3], off
	global_load_ushort v125, v[0:1], off
	global_load_dword v85, v[6:7], off
	global_load_ushort v124, v[4:5], off
	global_load_dword v78, v[10:11], off
	global_load_ushort v123, v[8:9], off
	global_load_dword v79, v[18:19], off
	global_load_ushort v121, v[16:17], off
	v_add_u32_e32 v0, s0, v97
	v_ashrrev_i32_e32 v1, 31, v0
	v_add_u32_e32 v4, s0, v99
	v_add_u32_e32 v8, s0, v101
	v_add_u32_e32 v16, s0, v103
	v_lshlrev_b64 v[0:1], 9, v[0:1]
	v_ashrrev_i32_e32 v5, 31, v4
	v_ashrrev_i32_e32 v9, 31, v8
	v_ashrrev_i32_e32 v17, 31, v16
	v_lshl_add_u64 v[0:1], v[0:1], 0, v[72:73]
	v_lshlrev_b64 v[4:5], 9, v[4:5]
	v_lshlrev_b64 v[8:9], 9, v[8:9]
	v_lshlrev_b64 v[16:17], 9, v[16:17]
	v_lshl_add_u64 v[2:3], v[0:1], 2, s[34:35]
	v_lshl_add_u64 v[4:5], v[4:5], 0, v[72:73]
	v_lshl_add_u64 v[8:9], v[8:9], 0, v[72:73]
	v_lshl_add_u64 v[16:17], v[16:17], 0, v[72:73]
	v_lshl_add_u64 v[0:1], v[0:1], 1, s[62:63]
	v_lshl_add_u64 v[6:7], v[4:5], 2, s[34:35]
	v_lshl_add_u64 v[4:5], v[4:5], 1, s[62:63]
	v_lshl_add_u64 v[10:11], v[8:9], 2, s[34:35]
	v_lshl_add_u64 v[8:9], v[8:9], 1, s[62:63]
	v_lshl_add_u64 v[18:19], v[16:17], 2, s[34:35]
	v_lshl_add_u64 v[16:17], v[16:17], 1, s[62:63]
	global_load_dword v82, v[2:3], off
	global_load_ushort v122, v[0:1], off
	global_load_dword v83, v[6:7], off
	global_load_ushort v120, v[4:5], off
	global_load_dword v76, v[10:11], off
	global_load_ushort v119, v[8:9], off
	global_load_dword v77, v[18:19], off
	global_load_ushort v118, v[16:17], off
	v_add_u32_e32 v0, s0, v105
	v_ashrrev_i32_e32 v1, 31, v0
	v_readlane_b32 s0, v254, 4
	v_lshlrev_b64 v[0:1], 10, v[0:1]
	v_readlane_b32 s1, v254, 5
	v_lshlrev_b32_e32 v6, 2, v93
	v_or_b32_e32 v7, v6, v13
	v_lshl_add_u64 v[0:1], s[0:1], 0, v[0:1]
	v_lshl_add_u64 v[0:1], v[0:1], 0, v[224:225]
	global_load_dwordx4 v[0:3], v[0:1], off
	v_lshlrev_b32_e32 v113, 2, v7
	v_and_b32_e32 v7, -16, v15
	v_lshl_add_u64 v[80:81], s[0:1], 0, v[224:225]
	v_or_b32_e32 v8, v7, v12
	s_movk_i32 s0, 0x110
	v_or_b32_e32 v10, 2, v6
	v_lshlrev_b32_e32 v4, 5, v14
	v_mul_lo_u32 v112, v8, s0
	v_cmp_gt_i32_e64 s[18:19], v10, v8
	v_or_b32_e32 v10, 3, v6
	s_movk_i32 s0, 0x60
	v_or_b32_e32 v7, v6, v7
	v_cmp_gt_i32_e64 s[20:21], v10, v8
	v_or_b32_e32 v10, 16, v6
	v_and_or_b32 v68, v4, s0, v12
	v_readlane_b32 s0, v251, 17
	v_cmp_gt_i32_e64 s[6:7], v10, v8
	v_or_b32_e32 v10, 17, v6
	v_mul_lo_u32 v89, v7, s0
	v_or_b32_e32 v5, v4, v69
	v_cmp_gt_i32_e64 s[16:17], v6, v8
	v_cmp_lt_i32_e64 s[14:15], v6, v8
	v_cmp_gt_i32_e64 s[8:9], v10, v8
	v_or_b32_e32 v10, 18, v6
	v_or_b32_e32 v6, 19, v6
	v_readlane_b32 s4, v254, 11
	v_add_u32_e32 v88, s0, v89
	v_add_u32_e32 v5, 0x12c00, v5
	v_or_b32_e32 v9, 0x12c00, v92
	v_mul_u32_u24_e32 v100, 0x110, v12
	v_cmp_gt_i32_e64 s[12:13], v6, v8
	v_mul_u32_u24_e32 v6, 0x110, v68
	v_lshlrev_b32_e32 v224, 2, v68
	v_readlane_b32 s5, v254, 12
	v_add_u32_e32 v87, s0, v88
	v_mov_b32_e32 v4, 0
	v_mul_u32_u24_e32 v116, 0x880, v93
	v_mul_u32_u24_e32 v115, 0x110, v32
	v_lshlrev_b32_e32 v108, 2, v31
	v_mul_u32_u24_e32 v117, 0x50, v12
	v_cmp_gt_i32_e64 s[10:11], v10, v8
	v_mul_u32_u24_e32 v90, 0x50, v68
	v_lshl_add_u64 v[70:71], s[4:5], 0, v[224:225]
	v_add_u32_e32 v86, s0, v87
	s_mov_b32 s50, 0
	s_movk_i32 s51, 0x8ff
	v_add_u32_e32 v91, v5, v100
	v_add_u32_e32 v75, v9, v6
	s_mov_b32 s61, 0
	v_mov_b32_e32 v5, v4
	v_mov_b32_e32 v6, v4
	v_mov_b32_e32 v7, v4
	v_mov_b32_e32 v36, v4
	v_mov_b32_e32 v37, v4
	v_mov_b32_e32 v38, v4
	v_mov_b32_e32 v39, v4
	v_mov_b32_e32 v12, v4
	v_mov_b32_e32 v13, v4
	v_mov_b32_e32 v14, v4
	v_mov_b32_e32 v15, v4
	v_mov_b32_e32 v40, v4
	v_mov_b32_e32 v41, v4
	v_mov_b32_e32 v42, v4
	v_mov_b32_e32 v43, v4
	v_mov_b32_e32 v16, v4
	v_mov_b32_e32 v17, v4
	v_mov_b32_e32 v18, v4
	v_mov_b32_e32 v19, v4
	v_mov_b32_e32 v44, v4
	v_mov_b32_e32 v45, v4
	v_mov_b32_e32 v46, v4
	v_mov_b32_e32 v47, v4
	v_mov_b32_e32 v20, v4
	v_mov_b32_e32 v21, v4
	v_mov_b32_e32 v22, v4
	v_mov_b32_e32 v23, v4
	v_mov_b32_e32 v48, v4
	v_mov_b32_e32 v49, v4
	v_mov_b32_e32 v50, v4
	v_mov_b32_e32 v51, v4
	v_mov_b32_e32 v24, v4
	v_mov_b32_e32 v25, v4
	v_mov_b32_e32 v26, v4
	v_mov_b32_e32 v27, v4
	v_mov_b32_e32 v52, v4
	v_mov_b32_e32 v53, v4
	v_mov_b32_e32 v54, v4
	v_mov_b32_e32 v55, v4
	v_mov_b32_e32 v28, v4
	v_mov_b32_e32 v29, v4
	v_mov_b32_e32 v30, v4
	v_mov_b32_e32 v31, v4
	v_mov_b32_e32 v56, v4
	v_mov_b32_e32 v57, v4
	v_mov_b32_e32 v58, v4
	v_mov_b32_e32 v59, v4
	v_mov_b32_e32 v32, v4
	v_mov_b32_e32 v33, v4
	v_mov_b32_e32 v34, v4
	v_mov_b32_e32 v35, v4
	v_mov_b32_e32 v60, v4
	v_mov_b32_e32 v61, v4
	v_mov_b32_e32 v62, v4
	v_mov_b32_e32 v63, v4
	v_mov_b32_e32 v8, v4
	v_mov_b32_e32 v9, v4
	v_mov_b32_e32 v10, v4
	v_mov_b32_e32 v11, v4
	v_mov_b32_e32 v64, v4
	v_mov_b32_e32 v65, v4
	v_mov_b32_e32 v66, v4
	v_mov_b32_e32 v67, v4
	s_waitcnt vmcnt(0)
	v_lshlrev_b32_e32 v222, 2, v72
	v_lshl_add_u32 v214, v114, 11, v222
	v_lshl_add_u32 v215, v94, 11, v222
	v_lshl_add_u32 v216, v95, 11, v222
	v_lshl_add_u32 v217, v96, 11, v222
	v_lshl_add_u32 v218, v97, 11, v222
	v_lshl_add_u32 v219, v99, 11, v222
	v_lshl_add_u32 v220, v101, 11, v222
	v_lshl_add_u32 v221, v103, 11, v222

; __device__ __forceinline__ void hgrn_phase(const Params& P, char* shm, int lbid) {
;     ...
;       __syncthreads();
;       const char* pb = shm + (c & 1) * PB;
;       {
;         const bf16x8 a = *(const bf16x8*)(pb + PB_KT + (16 * w + fr) * TSTR + quad * 16);
;         const float4 gl = *(const float4*)(pb + PB_GL + (16 * w + quad * 4) * 4);
; #pragma unroll
;         for (int vt = 0; vt < 8; ++vt) {
;           const bf16x8 bv = *(const bf16x8*)(pb + PB_VT + (vt * 16 + fr) * TSTR + quad * 16);
;           f32x4 t = __builtin_amdgcn_mfma_f32_16x16x32_bf16(a, bv, Sacc[vt], 0, 0, 0);
;           t[0] *= gl.x; t[1] *= gl.y; t[2] *= gl.z; t[3] *= gl.w;
;           Sacc[vt] = t;
;         }
;       }
;       {
;         const int tt = w >> 2, vt0 = (w & 3) * 2;
;         bf16x8 qf[4];
; #pragma unroll
;         for (int ks = 0; ks < 4; ++ks) qf[ks] = *(const bf16x8*)(pb + PB_Q + (tt * 16 + fr) * QSTR + (ks * 32 + quad * 8) * 2);
;         f32x4 AT[2];
; #pragma unroll
;         for (int st = 0; st < 2; ++st) {
;           f32x4 acc = f32x4{0.f, 0.f, 0.f, 0.f};
; #pragma unroll
;           for (int ks = 0; ks < 4; ++ks) {
;             const bf16x8 kf = *(const bf16x8*)(pb + PB_K + (st * 16 + fr) * QSTR + (ks * 32 + quad * 8) * 2);
;             acc = __builtin_amdgcn_mfma_f32_16x16x32_bf16(kf, qf[ks], acc, 0, 0, 0);
;           }
;           const int tpos = tt * 16 + fr;
; #pragma unroll
;           for (int jj = 0; jj < 4; ++jj)
;             if (st * 16 + quad * 4 + jj > tpos) acc[jj] = 0.0f;
;           AT[st] = acc;
;         }
.LBB0_922:
	s_lshl_b32 s98, s5, 11
	v_add_u32_e32 v0, s98, v214
	v_lshrrev_b32_e32 v1, 1, v0
	global_load_dword v84, v0, s[34:35]
	global_load_ushort v206, v1, s[62:63]
	v_add_u32_e32 v0, s98, v215
	v_lshrrev_b32_e32 v1, 1, v0
	global_load_dword v85, v0, s[34:35]
	global_load_ushort v207, v1, s[62:63]
	v_add_u32_e32 v0, s98, v216
	v_lshrrev_b32_e32 v1, 1, v0
	global_load_dword v78, v0, s[34:35]
	global_load_ushort v208, v1, s[62:63]
	v_add_u32_e32 v0, s98, v217
	v_lshrrev_b32_e32 v1, 1, v0
	global_load_dword v79, v0, s[34:35]
	global_load_ushort v209, v1, s[62:63]
	v_add_u32_e32 v0, s98, v218
	v_lshrrev_b32_e32 v1, 1, v0
	global_load_dword v82, v0, s[34:35]
	global_load_ushort v210, v1, s[62:63]
	v_add_u32_e32 v0, s98, v219
	v_lshrrev_b32_e32 v1, 1, v0
	global_load_dword v83, v0, s[34:35]
	global_load_ushort v211, v1, s[62:63]
	v_add_u32_e32 v0, s98, v220
	v_lshrrev_b32_e32 v1, 1, v0
	global_load_dword v76, v0, s[34:35]
	global_load_ushort v212, v1, s[62:63]
	v_add_u32_e32 v0, s98, v221
	v_lshrrev_b32_e32 v1, 1, v0
	global_load_dword v77, v0, s[34:35]
	global_load_ushort v213, v1, s[62:63]
	v_add_u32_e32 v0, s5, v105
	v_ashrrev_i32_e32 v1, 31, v0
	v_lshlrev_b64 v[0:1], 10, v[0:1]
	v_lshl_add_u64 v[0:1], v[80:81], 0, v[0:1]
	global_load_dwordx4 v[0:3], v[0:1], off
	s_bitcmp1_b32 s61, 0
	s_cselect_b32 s74, 0x9600, 0
	v_add_u32_e32 v4, s74, v74
	v_add_u32_e32 v126, v4, v92
	s_waitcnt lgkmcnt(0)
	s_barrier
	ds_read_b128 v[120:123], v126 offset:17408
	v_or_b32_e32 v124, s74, v92
	v_add_u32_e32 v125, v124, v117
	ds_read_b128 v[4:7], v125 offset:27648
	ds_read_b128 v[8:11], v125 offset:28928
	s_waitcnt lgkmcnt(0)
	v_mfma_f32_16x16x32_bf16 v[12:15], v[120:123], v[8:11], v[40:43]
	ds_read_b128 v[8:11], v125 offset:30208
	ds_read_b128 v[28:31], v125 offset:34048
	ds_read_b128 v[32:35], v125 offset:35328
	s_waitcnt lgkmcnt(2)
	v_mfma_f32_16x16x32_bf16 v[16:19], v[120:123], v[8:11], v[44:47]
	ds_read_b128 v[8:11], v125 offset:31488
	s_cmp_gt_u32 s61, 7
	s_mov_b64 s[0:1], -1
	v_mfma_f32_16x16x32_bf16 v[4:7], v[120:123], v[4:7], v[36:39]
	s_waitcnt lgkmcnt(0)
	v_mfma_f32_16x16x32_bf16 v[20:23], v[120:123], v[8:11], v[48:51]
	ds_read_b128 v[8:11], v125 offset:32768
	ds_read_b128 v[36:39], v125 offset:36608
	v_add_u32_e32 v125, v124, v100
	ds_read_b128 v[40:43], v125 offset:8704
	v_add_u32_e32 v124, v124, v112
	ds_read_b128 v[48:51], v124
	v_mfma_f32_16x16x32_bf16 v[28:31], v[120:123], v[28:31], v[56:59]
	s_waitcnt lgkmcnt(2)
	v_mfma_f32_16x16x32_bf16 v[56:59], v[120:123], v[36:39], v[64:67]
	ds_read_b128 v[36:39], v125 offset:8768
	ds_read_b128 v[44:47], v124 offset:64
	v_mfma_f32_16x16x32_bf16 v[8:11], v[120:123], v[8:11], v[52:55]
	s_waitcnt lgkmcnt(2)
	v_mfma_f32_16x16x32_bf16 v[52:55], v[40:43], v[48:51], 0
	v_mfma_f32_16x16x32_bf16 v[32:35], v[120:123], v[32:35], v[60:63]
	s_nop 2
	ds_read_b128 v[60:63], v125 offset:8832
	ds_read_b128 v[40:43], v124 offset:128
	ds_read_b128 v[64:67], v125 offset:13120
	ds_read_b128 v[120:123], v125 offset:13248
	s_waitcnt lgkmcnt(4)
	v_mfma_f32_16x16x32_bf16 v[36:39], v[36:39], v[44:47], v[52:55]
	s_nop 2
	ds_read_b128 v[52:55], v125 offset:8896
	s_waitcnt lgkmcnt(3)
	v_mfma_f32_16x16x32_bf16 v[60:63], v[60:63], v[40:43], v[36:39]
	s_nop 2
	ds_read_b128 v[36:39], v124 offset:192
	s_waitcnt lgkmcnt(0)
	v_mfma_f32_16x16x32_bf16 v[52:55], v[52:55], v[36:39], v[60:63]
	s_nop 2
	ds_read_b128 v[60:63], v125 offset:13056
	s_waitcnt lgkmcnt(0)
	v_mfma_f32_16x16x32_bf16 v[60:63], v[60:63], v[48:51], 0
	v_mfma_f32_16x16x32_bf16 v[60:63], v[64:67], v[44:47], v[60:63]
	ds_read_b128 v[64:67], v125 offset:13184
	s_waitcnt lgkmcnt(0)
	v_mfma_f32_16x16x32_bf16 v[60:63], v[64:67], v[40:43], v[60:63]
	v_add_u32_e32 v64, s74, v113
	ds_read_b128 v[64:67], v64 offset:37888
	v_mfma_f32_16x16x32_bf16 v[60:63], v[120:123], v[36:39], v[60:63]
	s_cbranch_scc0 .LBB0_924
	v_readlane_b32 s0, v251, 15
	s_add_i32 s5, s50, 0xffffff00
	v_readlane_b32 s1, v251, 16
	s_and_b64 s[0:1], s[0:1], exec
	s_cselect_b32 s0, s5, s51
	v_readlane_b32 s1, v254, 36
	s_add_i32 s5, s0, s1
	s_mov_b64 s[0:1], 0

; __device__ __forceinline__ void hgrn_phase(const Params& P, char* shm, int lbid) {
;     ...
;         const float4 gl = *(const float4*)(pb + PB_GL + (16 * w + quad * 4) * 4);
; #pragma unroll
;         for (int vt = 0; vt < 8; ++vt) {
;           const bf16x8 bv = *(const bf16x8*)(pb + PB_VT + (vt * 16 + fr) * TSTR + quad * 16);
;           f32x4 t = __builtin_amdgcn_mfma_f32_16x16x32_bf16(a, bv, Sacc[vt], 0, 0, 0);
;           t[0] *= gl.x; t[1] *= gl.y; t[2] *= gl.z; t[3] *= gl.w;
;           Sacc[vt] = t;
;         }
;       }
;       {
;         const int tt = w >> 2, vt0 = (w & 3) * 2;
;         bf16x8 qf[4];
; #pragma unroll
;         for (int ks = 0; ks < 4; ++ks) qf[ks] = *(const bf16x8*)(pb + PB_Q + (tt * 16 + fr) * QSTR + (ks * 32 + quad * 8) * 2);
;         f32x4 AT[2];
; #pragma unroll
;         for (int st = 0; st < 2; ++st) {
;           f32x4 acc = f32x4{0.f, 0.f, 0.f, 0.f};
; #pragma unroll
;           for (int ks = 0; ks < 4; ++ks) {
;             const bf16x8 kf = *(const bf16x8*)(pb + PB_K + (st * 16 + fr) * QSTR + (ks * 32 + quad * 8) * 2);
;             acc = __builtin_amdgcn_mfma_f32_16x16x32_bf16(kf, qf[ks], acc, 0, 0, 0);
;           }
;           const int tpos = tt * 16 + fr;
; #pragma unroll
;           for (int jj = 0; jj < 4; ++jj)
;             if (st * 16 + quad * 4 + jj > tpos) acc[jj] = 0.0f;
;           AT[st] = acc;
;         }
;         u32x4 ap;
;         ap.x = pack2(AT[0][0], AT[0][1]); ap.y = pack2(AT[0][2], AT[0][3]);
;         ap.z = pack2(AT[1][0], AT[1][1]); ap.w = pack2(AT[1][2], AT[1][3]);
;         const int r0 = HG_R0(c);
; #pragma unroll
;         for (int e = 0; e < 2; ++e) {
;           const int vt = vt0 + e;
;           f32x4 O = f32x4{0.f, 0.f, 0.f, 0.f};
; #pragma unroll
;           for (int ks = 0; ks < 4; ++ks) {
;             const bf16x8 sf = *(const bf16x8*)(sb + (vt * 16 + fr) * QSTR + (ks * 32 + quad * 8) * 2);
;             O = __builtin_amdgcn_mfma_f32_16x16x32_bf16(qf[ks], sf, O, 0, 0, 0);
;           }
;           const char* vp = pb + PB_VT + (vt * 16 + fr) * TSTR + quad * 8;
;           const u32x2 lo = *(const u32x2*)vp, hi = *(const u32x2*)(vp + 32);
;           u32x4 bp; bp.x = lo.x; bp.y = lo.y; bp.z = hi.x; bp.w = hi.y;
;           O = __builtin_amdgcn_mfma_f32_16x16x32_bf16(__builtin_bit_cast(bf16x8, ap), __builtin_bit_cast(bf16x8, bp), O, 0, 0, 0);
; #pragma unroll
.LBB0_926:
	s_nop 0
	s_nop 0
	s_nop 0
	s_nop 0
	s_waitcnt lgkmcnt(0)
	v_add3_u32 v204, s74, v69, v90
	ds_read_b128 v[168:171], v75
	ds_read_b128 v[172:175], v75 offset:64
	ds_read_b128 v[176:179], v75 offset:128
	ds_read_b128 v[180:183], v75 offset:192
	v_add_u32_e32 v205, 0x6800, v204
	ds_read2_b64 v[200:203], v205 offset0:128 offset1:132
	ds_read_b128 v[184:187], v75 offset:4352
	ds_read_b128 v[188:191], v75 offset:4416
	ds_read_b128 v[192:195], v75 offset:4480
	ds_read_b128 v[196:199], v75 offset:4544
	v_add_u32_e32 v204, 0x7000, v204
	ds_read2_b64 v[130:133], v204 offset0:32 offset1:36
	v_pk_mul_f32 v[24:25], v[64:65], v[8:9]
	v_pk_mul_f32 v[8:9], v[64:65], v[56:57]
	v_mov_b32_e32 v56, s75
	v_cndmask_b32_e64 v56, v52, v56, s[16:17]
	v_cndmask_b32_e64 v56, v56, v52, s[14:15]
	v_mov_b32_e32 v52, s75
	s_nop 0
	s_nop 0
	s_nop 0
	s_nop 0
	v_pk_mul_f32 v[26:27], v[66:67], v[10:11]
	v_pk_mul_f32 v[10:11], v[66:67], v[58:59]
	v_cndmask_b32_e64 v53, 0, v53, s[14:15]
	v_cndmask_b32_e64 v54, v54, 0, s[18:19]
	v_cndmask_b32_e64 v55, v55, 0, s[20:21]
	v_cndmask_b32_e64 v57, v60, v52, s[6:7]
	v_cndmask_b32_e64 v58, v61, 0, s[8:9]
	v_cndmask_b32_e64 v59, v62, 0, s[10:11]
	v_cndmask_b32_e64 v60, v63, 0, s[12:13]
	v_cvt_pk_bf16_f32 v52, v56, v53
	v_cvt_pk_bf16_f32 v53, v54, v55
	v_cvt_pk_bf16_f32 v54, v57, v58
	v_cvt_pk_bf16_f32 v55, v59, v60
	s_nop 0
	s_nop 0
	s_waitcnt lgkmcnt(9)
	v_mfma_f32_16x16x32_bf16 v[56:59], v[48:51], v[168:171], 0
	s_nop 0
	s_nop 0
	s_nop 0
	s_nop 0
	v_add3_u32 v127, s74, v69, v90
	s_waitcnt lgkmcnt(8)
	v_mfma_f32_16x16x32_bf16 v[56:59], v[44:47], v[172:175], v[56:59]
	s_nop 0
	v_pk_mul_f32 v[4:5], v[64:65], v[4:5]
	v_pk_mul_f32 v[12:13], v[64:65], v[12:13]
	s_waitcnt lgkmcnt(7)
	v_mfma_f32_16x16x32_bf16 v[56:59], v[40:43], v[176:179], v[56:59]
	s_nop 0
	v_pk_mul_f32 v[16:17], v[64:65], v[16:17]
	v_pk_mul_f32 v[20:21], v[64:65], v[20:21]
	s_waitcnt lgkmcnt(6)
	v_mfma_f32_16x16x32_bf16 v[56:59], v[36:39], v[180:183], v[56:59]
	s_nop 0
	s_nop 0
	v_pk_mul_f32 v[28:29], v[64:65], v[28:29]
	s_waitcnt lgkmcnt(5)
	v_mfma_f32_16x16x32_bf16 v[56:59], v[52:55], v[200:203], v[56:59]
	v_add_u32_e32 v60, s5, v89
	v_ashrrev_i32_e32 v61, 31, v60
	v_add_u32_e32 v62, s5, v88
	v_lshlrev_b64 v[60:61], 11, v[60:61]
	v_ashrrev_i32_e32 v63, 31, v62
	v_lshl_add_u64 v[60:61], v[70:71], 0, v[60:61]
	v_lshlrev_b64 v[62:63], 11, v[62:63]
	s_nop 0
	global_store_dword v[60:61], v56, off
	v_lshl_add_u64 v[62:63], v[70:71], 0, v[62:63]
	v_add_u32_e32 v56, s5, v87
	global_store_dword v[62:63], v57, off
	v_ashrrev_i32_e32 v57, 31, v56
	v_lshlrev_b64 v[56:57], 11, v[56:57]
	v_pk_mul_f32 v[32:33], v[64:65], v[32:33]
	v_lshl_add_u64 v[64:65], v[70:71], 0, v[56:57]
	v_add_u32_e32 v56, s5, v86
	v_ashrrev_i32_e32 v57, 31, v56
	v_lshlrev_b64 v[56:57], 11, v[56:57]
	v_pk_mul_f32 v[6:7], v[66:67], v[6:7]
	v_pk_mul_f32 v[14:15], v[66:67], v[14:15]
	v_pk_mul_f32 v[18:19], v[66:67], v[18:19]
	v_pk_mul_f32 v[22:23], v[66:67], v[22:23]
	v_pk_mul_f32 v[30:31], v[66:67], v[30:31]
	v_pk_mul_f32 v[34:35], v[66:67], v[34:35]
	v_lshl_add_u64 v[66:67], v[70:71], 0, v[56:57]
	global_store_dword v[64:65], v58, off
	global_store_dword v[66:67], v59, off
	s_nop 0
	s_waitcnt lgkmcnt(4)
	v_mfma_f32_16x16x32_bf16 v[48:51], v[48:51], v[184:187], 0
	s_nop 0
	s_add_i32 s50, s50, 32
	s_sub_i32 s51, s51, 32
	s_waitcnt lgkmcnt(3)
	v_mfma_f32_16x16x32_bf16 v[44:47], v[44:47], v[188:191], v[48:51]
	s_nop 0
	s_nop 1
	s_nop 0
	s_nop 0
	s_nop 0
	s_waitcnt lgkmcnt(2)
	v_mfma_f32_16x16x32_bf16 v[40:43], v[40:43], v[192:195], v[44:47]
	s_nop 2
	s_nop 0
	s_cmpk_eq_i32 s50, 0x8c0
	s_waitcnt lgkmcnt(1)
	v_mfma_f32_16x16x32_bf16 v[36:39], v[36:39], v[196:199], v[40:43]
	s_nop 2
	s_nop 0
	s_nop 0
	s_waitcnt lgkmcnt(0)
	v_mfma_f32_16x16x32_bf16 v[36:39], v[52:55], v[130:133], v[36:39]
	s_nop 7
	global_store_dword v[60:61], v36, off offset:64
	global_store_dword v[62:63], v37, off offset:64
	global_store_dword v[64:65], v38, off offset:64
	global_store_dword v[66:67], v39, off offset:64
	s_barrier
	s_waitcnt vmcnt(9)
	v_mov_b32_e32 v125, v206
	v_mov_b32_e32 v124, v207
	v_mov_b32_e32 v123, v208
	v_mov_b32_e32 v121, v209
	v_mov_b32_e32 v120, v211
	v_mov_b32_e32 v119, v212
	v_mov_b32_e32 v122, v210
	v_mov_b32_e32 v118, v213
	s_cbranch_scc1 .LBB0_928
	s_mov_b32 s61, s4
	v_mov_b64_e32 v[36:37], v[4:5]
	v_mov_b64_e32 v[38:39], v[6:7]
	v_mov_b64_e32 v[40:41], v[12:13]
	v_mov_b64_e32 v[42:43], v[14:15]
	v_mov_b64_e32 v[44:45], v[16:17]
	v_mov_b64_e32 v[46:47], v[18:19]
	v_mov_b64_e32 v[48:49], v[20:21]
	v_mov_b64_e32 v[50:51], v[22:23]
	v_mov_b64_e32 v[52:53], v[24:25]
	v_mov_b64_e32 v[54:55], v[26:27]
	v_mov_b64_e32 v[56:57], v[28:29]
	v_mov_b64_e32 v[58:59], v[30:31]
	v_mov_b64_e32 v[60:61], v[32:33]
	v_mov_b64_e32 v[62:63], v[34:35]
	v_mov_b64_e32 v[64:65], v[8:9]
	v_mov_b64_e32 v[66:67], v[10:11]
	s_branch .LBB0_908
